# v17 plus removal of 128 redundant canonicalize v_max ops in the P5 squared-relu epilogue
# speedup vs baseline: 1.0060x; 1.0060x over previous
.LBB0_697:
	v_max_f32_e32 v124, 0, v124
	v_max_f32_e32 v125, 0, v125
	v_pk_mul_f32 v[152:153], v[124:125], v[124:125]
	v_lshl_or_b32 v142, s12, 8, v145
	v_lshl_add_u32 v148, s13, 8, v1
	v_max_f32_e32 v126, 0, v126
	v_ashrrev_i32_e32 v143, 31, v142
	v_ashrrev_i32_e32 v149, 31, v148
	v_max_f32_e32 v128, 0, v128
	v_max_f32_e32 v129, 0, v129
	v_max_f32_e32 v124, 0, v130
	v_max_f32_e32 v125, 0, v131
	v_max_f32_e32 v127, 0, v127
	v_lshl_add_u64 v[150:151], v[142:143], 1, s[38:39]
	v_lshlrev_b64 v[142:143], 14, v[148:149]
	v_pk_mul_f32 v[128:129], v[128:129], v[128:129]
	v_pk_mul_f32 v[130:131], v[124:125], v[124:125]
	v_pk_mul_f32 v[154:155], v[126:127], v[126:127]
	v_lshl_add_u64 v[142:143], v[150:151], 0, v[142:143]
	v_cvt_pk_bf16_f32 v124, v128, v129
	v_cvt_pk_bf16_f32 v125, v130, v131
	v_cvt_pk_bf16_f32 v126, v152, v153
	v_cvt_pk_bf16_f32 v127, v154, v155
	v_max_f32_e32 v116, 0, v116
	v_max_f32_e32 v117, 0, v117
	ds_bpermute_b32 v222, v231, v124
	ds_bpermute_b32 v223, v231, v125
	ds_bpermute_b32 v224, v231, v126
	ds_bpermute_b32 v225, v231, v127
	v_pk_mul_f32 v[124:125], v[116:117], v[116:117]
	v_max_f32_e32 v118, 0, v118
	v_max_f32_e32 v120, 0, v120
	v_max_f32_e32 v121, 0, v121
	v_max_f32_e32 v116, 0, v122
	v_max_f32_e32 v117, 0, v123
	v_max_f32_e32 v119, 0, v119
	v_pk_mul_f32 v[120:121], v[120:121], v[120:121]
	v_pk_mul_f32 v[122:123], v[116:117], v[116:117]
	v_pk_mul_f32 v[126:127], v[118:119], v[118:119]
	v_cvt_pk_bf16_f32 v116, v120, v121
	v_cvt_pk_bf16_f32 v117, v122, v123
	v_cvt_pk_bf16_f32 v118, v124, v125
	v_cvt_pk_bf16_f32 v119, v126, v127
	v_max_f32_e32 v108, 0, v108
	v_max_f32_e32 v109, 0, v109
	s_waitcnt lgkmcnt(0)
	global_store_dwordx4 v[142:143], v[222:225], off
	ds_bpermute_b32 v226, v231, v116
	ds_bpermute_b32 v227, v231, v117
	ds_bpermute_b32 v228, v231, v118
	ds_bpermute_b32 v229, v231, v119
	v_pk_mul_f32 v[118:119], v[108:109], v[108:109]
	v_or_b32_e32 v116, 16, v148
	v_max_f32_e32 v110, 0, v110
	v_ashrrev_i32_e32 v117, 31, v116
	v_max_f32_e32 v112, 0, v112
	v_max_f32_e32 v113, 0, v113
	v_max_f32_e32 v108, 0, v114
	v_max_f32_e32 v109, 0, v115
	v_max_f32_e32 v111, 0, v111
	v_lshlrev_b64 v[116:117], 14, v[116:117]
	v_pk_mul_f32 v[112:113], v[112:113], v[112:113]
	v_pk_mul_f32 v[114:115], v[108:109], v[108:109]
	v_pk_mul_f32 v[120:121], v[110:111], v[110:111]
	v_lshl_add_u64 v[116:117], v[150:151], 0, v[116:117]
	v_cvt_pk_bf16_f32 v108, v112, v113
	v_cvt_pk_bf16_f32 v109, v114, v115
	v_cvt_pk_bf16_f32 v110, v118, v119
	v_cvt_pk_bf16_f32 v111, v120, v121
	v_max_f32_e32 v100, 0, v100
	v_max_f32_e32 v101, 0, v101
	s_waitcnt lgkmcnt(0)
	global_store_dwordx4 v[142:143], v[226:229], off offset:256
	ds_bpermute_b32 v222, v231, v108
	ds_bpermute_b32 v223, v231, v109
	ds_bpermute_b32 v224, v231, v110
	ds_bpermute_b32 v225, v231, v111
	v_pk_mul_f32 v[108:109], v[100:101], v[100:101]
	v_max_f32_e32 v102, 0, v102
	v_max_f32_e32 v104, 0, v104
	v_max_f32_e32 v105, 0, v105
	v_max_f32_e32 v100, 0, v106
	v_max_f32_e32 v101, 0, v107
	v_max_f32_e32 v103, 0, v103
	v_pk_mul_f32 v[104:105], v[104:105], v[104:105]
	v_pk_mul_f32 v[106:107], v[100:101], v[100:101]
	v_pk_mul_f32 v[110:111], v[102:103], v[102:103]
	v_cvt_pk_bf16_f32 v100, v104, v105
	v_cvt_pk_bf16_f32 v101, v106, v107
	v_cvt_pk_bf16_f32 v102, v108, v109
	v_cvt_pk_bf16_f32 v103, v110, v111
	v_max_f32_e32 v92, 0, v92
	v_max_f32_e32 v93, 0, v93
	s_waitcnt lgkmcnt(0)
	global_store_dwordx4 v[116:117], v[222:225], off
	ds_bpermute_b32 v226, v231, v100
	ds_bpermute_b32 v227, v231, v101
	ds_bpermute_b32 v228, v231, v102
	ds_bpermute_b32 v229, v231, v103
	v_pk_mul_f32 v[102:103], v[92:93], v[92:93]
	v_or_b32_e32 v100, 32, v148
	v_max_f32_e32 v94, 0, v94
	v_ashrrev_i32_e32 v101, 31, v100
	v_max_f32_e32 v96, 0, v96
	v_max_f32_e32 v97, 0, v97
	v_max_f32_e32 v92, 0, v98
	v_max_f32_e32 v93, 0, v99
	v_max_f32_e32 v95, 0, v95
	v_lshlrev_b64 v[100:101], 14, v[100:101]
	v_pk_mul_f32 v[96:97], v[96:97], v[96:97]
	v_pk_mul_f32 v[98:99], v[92:93], v[92:93]
	v_pk_mul_f32 v[104:105], v[94:95], v[94:95]
	v_lshl_add_u64 v[100:101], v[150:151], 0, v[100:101]
	v_cvt_pk_bf16_f32 v92, v96, v97
	v_cvt_pk_bf16_f32 v93, v98, v99
	v_cvt_pk_bf16_f32 v94, v102, v103
	v_cvt_pk_bf16_f32 v95, v104, v105
	v_max_f32_e32 v84, 0, v84
	v_max_f32_e32 v85, 0, v85
	s_waitcnt lgkmcnt(0)
	global_store_dwordx4 v[116:117], v[226:229], off offset:256
	ds_bpermute_b32 v222, v231, v92
	ds_bpermute_b32 v223, v231, v93
	ds_bpermute_b32 v224, v231, v94
	ds_bpermute_b32 v225, v231, v95
	v_pk_mul_f32 v[92:93], v[84:85], v[84:85]
	v_max_f32_e32 v86, 0, v86
	v_max_f32_e32 v88, 0, v88
	v_max_f32_e32 v89, 0, v89
	v_max_f32_e32 v84, 0, v90
	v_max_f32_e32 v85, 0, v91
	v_max_f32_e32 v87, 0, v87
	v_pk_mul_f32 v[88:89], v[88:89], v[88:89]
	v_pk_mul_f32 v[90:91], v[84:85], v[84:85]
	v_pk_mul_f32 v[94:95], v[86:87], v[86:87]
	v_cvt_pk_bf16_f32 v84, v88, v89
	v_cvt_pk_bf16_f32 v85, v90, v91
	v_cvt_pk_bf16_f32 v86, v92, v93
	v_cvt_pk_bf16_f32 v87, v94, v95
	v_max_f32_e32 v76, 0, v76
	v_max_f32_e32 v77, 0, v77
	s_waitcnt lgkmcnt(0)
	global_store_dwordx4 v[100:101], v[222:225], off
	ds_bpermute_b32 v226, v231, v84
	ds_bpermute_b32 v227, v231, v85
	ds_bpermute_b32 v228, v231, v86
	ds_bpermute_b32 v229, v231, v87
	v_pk_mul_f32 v[86:87], v[76:77], v[76:77]
	v_or_b32_e32 v84, 48, v148
	v_max_f32_e32 v78, 0, v78
	v_ashrrev_i32_e32 v85, 31, v84
	v_max_f32_e32 v80, 0, v80
	v_max_f32_e32 v81, 0, v81
	v_max_f32_e32 v76, 0, v82
	v_max_f32_e32 v77, 0, v83
	v_max_f32_e32 v79, 0, v79
	v_lshlrev_b64 v[84:85], 14, v[84:85]
	v_pk_mul_f32 v[80:81], v[80:81], v[80:81]
	v_pk_mul_f32 v[82:83], v[76:77], v[76:77]
	v_pk_mul_f32 v[88:89], v[78:79], v[78:79]
	v_lshl_add_u64 v[84:85], v[150:151], 0, v[84:85]
	v_cvt_pk_bf16_f32 v76, v80, v81
	v_cvt_pk_bf16_f32 v77, v82, v83
	v_cvt_pk_bf16_f32 v78, v86, v87
	v_cvt_pk_bf16_f32 v79, v88, v89
	v_max_f32_e32 v68, 0, v68
	v_max_f32_e32 v69, 0, v69
	s_waitcnt lgkmcnt(0)
	global_store_dwordx4 v[100:101], v[226:229], off offset:256
	ds_bpermute_b32 v222, v231, v76
	ds_bpermute_b32 v223, v231, v77
	ds_bpermute_b32 v224, v231, v78
	ds_bpermute_b32 v225, v231, v79
	v_pk_mul_f32 v[76:77], v[68:69], v[68:69]
	v_max_f32_e32 v70, 0, v70
	v_max_f32_e32 v72, 0, v72
	v_max_f32_e32 v73, 0, v73
	v_max_f32_e32 v68, 0, v74
	v_max_f32_e32 v69, 0, v75
	v_max_f32_e32 v71, 0, v71
	v_pk_mul_f32 v[72:73], v[72:73], v[72:73]
	v_pk_mul_f32 v[74:75], v[68:69], v[68:69]
	v_pk_mul_f32 v[78:79], v[70:71], v[70:71]
	v_cvt_pk_bf16_f32 v68, v72, v73
	v_cvt_pk_bf16_f32 v69, v74, v75
	v_cvt_pk_bf16_f32 v70, v76, v77
	v_cvt_pk_bf16_f32 v71, v78, v79
	v_max_f32_e32 v60, 0, v60
	v_max_f32_e32 v61, 0, v61
	s_waitcnt lgkmcnt(0)
	global_store_dwordx4 v[84:85], v[222:225], off
	ds_bpermute_b32 v226, v231, v68
	ds_bpermute_b32 v227, v231, v69
	ds_bpermute_b32 v228, v231, v70
	ds_bpermute_b32 v229, v231, v71
	v_pk_mul_f32 v[70:71], v[60:61], v[60:61]
	s_mov_b64 s[12:13], 0x200000
	v_max_f32_e32 v64, 0, v64
	v_max_f32_e32 v65, 0, v65
	v_max_f32_e32 v62, 0, v62
	v_lshl_add_u64 v[68:69], v[142:143], 0, s[12:13]
	v_pk_mul_f32 v[64:65], v[64:65], v[64:65]
	v_max_f32_e32 v60, 0, v66
	v_max_f32_e32 v61, 0, v67
	v_max_f32_e32 v63, 0, v63
	s_mov_b32 s12, 0x200000
	v_pk_mul_f32 v[66:67], v[60:61], v[60:61]
	v_pk_mul_f32 v[72:73], v[62:63], v[62:63]
	v_cvt_pk_bf16_f32 v60, v64, v65
	v_add_co_u32_e32 v64, vcc, s12, v142
	v_cvt_pk_bf16_f32 v61, v66, v67
	v_cvt_pk_bf16_f32 v62, v70, v71
	v_cvt_pk_bf16_f32 v63, v72, v73
	v_addc_co_u32_e32 v65, vcc, 0, v143, vcc
	v_max_f32_e32 v52, 0, v52
	v_max_f32_e32 v53, 0, v53
	s_waitcnt lgkmcnt(0)
	global_store_dwordx4 v[84:85], v[226:229], off offset:256
	ds_bpermute_b32 v222, v231, v60
	ds_bpermute_b32 v223, v231, v61
	ds_bpermute_b32 v224, v231, v62
	ds_bpermute_b32 v225, v231, v63
	v_pk_mul_f32 v[60:61], v[52:53], v[52:53]
	v_max_f32_e32 v54, 0, v54
	v_max_f32_e32 v56, 0, v56
	v_max_f32_e32 v57, 0, v57
	v_max_f32_e32 v52, 0, v58
	v_max_f32_e32 v53, 0, v59
	v_max_f32_e32 v55, 0, v55
	v_pk_mul_f32 v[56:57], v[56:57], v[56:57]
	v_pk_mul_f32 v[58:59], v[52:53], v[52:53]
	v_pk_mul_f32 v[62:63], v[54:55], v[54:55]
	v_cvt_pk_bf16_f32 v52, v56, v57
	v_cvt_pk_bf16_f32 v53, v58, v59
	v_cvt_pk_bf16_f32 v54, v60, v61
	v_cvt_pk_bf16_f32 v55, v62, v63
	v_max_f32_e32 v44, 0, v44
	v_max_f32_e32 v45, 0, v45
	s_waitcnt lgkmcnt(0)
	global_store_dwordx4 v[64:65], v[222:225], off
	ds_bpermute_b32 v226, v231, v52
	ds_bpermute_b32 v227, v231, v53
	ds_bpermute_b32 v228, v231, v54
	ds_bpermute_b32 v229, v231, v55
	v_pk_mul_f32 v[54:55], v[44:45], v[44:45]
	s_mov_b64 s[12:13], 0x240000
	v_max_f32_e32 v48, 0, v48
	v_max_f32_e32 v49, 0, v49
	v_max_f32_e32 v46, 0, v46
	v_lshl_add_u64 v[52:53], v[142:143], 0, s[12:13]
	v_pk_mul_f32 v[48:49], v[48:49], v[48:49]
	v_max_f32_e32 v44, 0, v50
	v_max_f32_e32 v45, 0, v51
	v_max_f32_e32 v47, 0, v47
	s_mov_b32 s12, 0x240000
	v_pk_mul_f32 v[50:51], v[44:45], v[44:45]
	v_pk_mul_f32 v[56:57], v[46:47], v[46:47]
	v_cvt_pk_bf16_f32 v44, v48, v49
	v_add_co_u32_e32 v48, vcc, s12, v142
	v_cvt_pk_bf16_f32 v45, v50, v51
	v_cvt_pk_bf16_f32 v46, v54, v55
	v_cvt_pk_bf16_f32 v47, v56, v57
	v_addc_co_u32_e32 v49, vcc, 0, v143, vcc
	v_max_f32_e32 v36, 0, v36
	v_max_f32_e32 v37, 0, v37
	s_waitcnt lgkmcnt(0)
	global_store_dwordx4 v[68:69], v[226:229], off offset:256
	ds_bpermute_b32 v222, v231, v44
	ds_bpermute_b32 v223, v231, v45
	ds_bpermute_b32 v224, v231, v46
	ds_bpermute_b32 v225, v231, v47
	v_pk_mul_f32 v[44:45], v[36:37], v[36:37]
	v_max_f32_e32 v38, 0, v38
	v_max_f32_e32 v40, 0, v40
	v_max_f32_e32 v41, 0, v41
	v_max_f32_e32 v36, 0, v42
	v_max_f32_e32 v37, 0, v43
	v_max_f32_e32 v39, 0, v39
	v_pk_mul_f32 v[40:41], v[40:41], v[40:41]
	v_pk_mul_f32 v[42:43], v[36:37], v[36:37]
	v_pk_mul_f32 v[46:47], v[38:39], v[38:39]
	v_cvt_pk_bf16_f32 v36, v40, v41
	v_cvt_pk_bf16_f32 v37, v42, v43
	v_cvt_pk_bf16_f32 v38, v44, v45
	v_cvt_pk_bf16_f32 v39, v46, v47
	v_max_f32_e32 v28, 0, v28
	v_max_f32_e32 v29, 0, v29
	s_waitcnt lgkmcnt(0)
	global_store_dwordx4 v[48:49], v[222:225], off
	ds_bpermute_b32 v226, v231, v36
	ds_bpermute_b32 v227, v231, v37
	ds_bpermute_b32 v228, v231, v38
	ds_bpermute_b32 v229, v231, v39
	v_pk_mul_f32 v[38:39], v[28:29], v[28:29]
	s_mov_b64 s[12:13], 0x280000
	v_max_f32_e32 v32, 0, v32
	v_max_f32_e32 v33, 0, v33
	v_max_f32_e32 v30, 0, v30
	v_lshl_add_u64 v[36:37], v[142:143], 0, s[12:13]
	v_pk_mul_f32 v[32:33], v[32:33], v[32:33]
	v_max_f32_e32 v28, 0, v34
	v_max_f32_e32 v29, 0, v35
	v_max_f32_e32 v31, 0, v31
	s_mov_b32 s12, 0x280000
	v_pk_mul_f32 v[34:35], v[28:29], v[28:29]
	v_pk_mul_f32 v[40:41], v[30:31], v[30:31]
	v_cvt_pk_bf16_f32 v28, v32, v33
	v_add_co_u32_e32 v32, vcc, s12, v142
	v_cvt_pk_bf16_f32 v29, v34, v35
	v_cvt_pk_bf16_f32 v30, v38, v39
	v_cvt_pk_bf16_f32 v31, v40, v41
	v_addc_co_u32_e32 v33, vcc, 0, v143, vcc
	v_max_f32_e32 v20, 0, v20
	v_max_f32_e32 v21, 0, v21
	s_waitcnt lgkmcnt(0)
	global_store_dwordx4 v[52:53], v[226:229], off offset:256
	ds_bpermute_b32 v222, v231, v28
	ds_bpermute_b32 v223, v231, v29
	ds_bpermute_b32 v224, v231, v30
	ds_bpermute_b32 v225, v231, v31
	v_pk_mul_f32 v[28:29], v[20:21], v[20:21]
	v_max_f32_e32 v22, 0, v22
	v_max_f32_e32 v24, 0, v24
	v_max_f32_e32 v25, 0, v25
	v_max_f32_e32 v20, 0, v26
	v_max_f32_e32 v21, 0, v27
	v_max_f32_e32 v23, 0, v23
	v_pk_mul_f32 v[24:25], v[24:25], v[24:25]
	v_pk_mul_f32 v[26:27], v[20:21], v[20:21]
	v_pk_mul_f32 v[30:31], v[22:23], v[22:23]
	v_cvt_pk_bf16_f32 v20, v24, v25
	v_cvt_pk_bf16_f32 v21, v26, v27
	v_cvt_pk_bf16_f32 v22, v28, v29
	v_cvt_pk_bf16_f32 v23, v30, v31
	v_max_f32_e32 v12, 0, v12
	v_max_f32_e32 v13, 0, v13
	s_waitcnt lgkmcnt(0)
	global_store_dwordx4 v[32:33], v[222:225], off
	ds_bpermute_b32 v226, v231, v20
	ds_bpermute_b32 v227, v231, v21
	ds_bpermute_b32 v228, v231, v22
	ds_bpermute_b32 v229, v231, v23
	v_pk_mul_f32 v[22:23], v[12:13], v[12:13]
	s_mov_b64 s[12:13], 0x2c0000
	v_max_f32_e32 v16, 0, v16
	v_max_f32_e32 v17, 0, v17
	v_max_f32_e32 v14, 0, v14
	v_lshl_add_u64 v[20:21], v[142:143], 0, s[12:13]
	v_pk_mul_f32 v[16:17], v[16:17], v[16:17]
	v_max_f32_e32 v12, 0, v18
	v_max_f32_e32 v13, 0, v19
	v_max_f32_e32 v15, 0, v15
	s_mov_b32 s12, 0x2c0000
	v_pk_mul_f32 v[18:19], v[12:13], v[12:13]
	v_pk_mul_f32 v[24:25], v[14:15], v[14:15]
	v_cvt_pk_bf16_f32 v12, v16, v17
	v_add_co_u32_e32 v16, vcc, s12, v142
	v_cvt_pk_bf16_f32 v13, v18, v19
	v_cvt_pk_bf16_f32 v14, v22, v23
	v_cvt_pk_bf16_f32 v15, v24, v25
	v_addc_co_u32_e32 v17, vcc, 0, v143, vcc
	v_max_f32_e32 v4, 0, v4
	v_max_f32_e32 v5, 0, v5
	s_waitcnt lgkmcnt(0)
	global_store_dwordx4 v[36:37], v[226:229], off offset:256
	ds_bpermute_b32 v222, v231, v12
	ds_bpermute_b32 v223, v231, v13
	ds_bpermute_b32 v224, v231, v14
	ds_bpermute_b32 v225, v231, v15
	v_pk_mul_f32 v[12:13], v[4:5], v[4:5]
	v_max_f32_e32 v6, 0, v6
	v_max_f32_e32 v8, 0, v8
	v_max_f32_e32 v9, 0, v9
	v_max_f32_e32 v4, 0, v10
	v_max_f32_e32 v5, 0, v11
	v_max_f32_e32 v7, 0, v7
	v_pk_mul_f32 v[8:9], v[8:9], v[8:9]
	v_pk_mul_f32 v[10:11], v[4:5], v[4:5]
	v_pk_mul_f32 v[14:15], v[6:7], v[6:7]
	v_cvt_pk_bf16_f32 v4, v8, v9
	v_cvt_pk_bf16_f32 v5, v10, v11
	v_cvt_pk_bf16_f32 v6, v12, v13
	v_cvt_pk_bf16_f32 v7, v14, v15
	s_andn2_b64 vcc, exec, s[36:37]
	s_mov_b64 s[36:37], -1
	s_waitcnt lgkmcnt(0)
	global_store_dwordx4 v[16:17], v[222:225], off
	ds_bpermute_b32 v226, v231, v4
	ds_bpermute_b32 v227, v231, v5
	ds_bpermute_b32 v228, v231, v6
	ds_bpermute_b32 v229, v231, v7
	s_waitcnt lgkmcnt(0)
	global_store_dwordx4 v[20:21], v[226:229], off offset:256
	s_cbranch_vccnz .LBB0_690
	s_andn2_b64 vcc, exec, s[0:1]
	s_cbranch_vccnz .LBB0_689
	s_barrier
	s_branch .LBB0_689
